# XCD barrier: skip the L2 write-back after pure-GEMM phases whose epilogue stores are all write-through
# baseline (speedup 1.0000x reference)
; __device__ __forceinline__ unsigned xb_add(unsigned* p, unsigned v) { return __hip_atomic_fetch_add(p, v, __ATOMIC_RELAXED, __HIP_MEMORY_SCOPE_AGENT); }
; __device__ __forceinline__ void xcd_barrier(const XcdBarrier& b) {
;     ...
;         if (old + 1u == (gen + 1u) * nloc) {
;             __builtin_amdgcn_fence(__ATOMIC_RELEASE, "agent");
;             asm volatile("s_waitcnt vmcnt(0)" ::: "memory");
;             const unsigned og = xb_add(&bar[XB_TOP], 1u);
.LBB0_583:
	s_andn2_saveexec_b64 s[10:11], s[12:13]
	s_cbranch_execz .LBB0_603
	s_mov_b64 s[12:13], exec
	s_mov_b32 s10, 0x18e20c71
	s_bitcmp1_b32 s10, s7
	s_cbranch_scc0 .Lxb_nowb
	buffer_wbl2 sc1
.Lxb_nowb:
	s_waitcnt lgkmcnt(0)
	s_waitcnt vmcnt(0)
	v_mbcnt_lo_u32_b32 v1, s12, 0
	v_mbcnt_hi_u32_b32 v1, s13, v1
	v_cmp_eq_u32_e32 vcc, 0, v1
	s_and_saveexec_b64 s[38:39], vcc
	s_cbranch_execz .LBB0_586
	s_bcnt1_i32_b64 s10, s[12:13]
	v_mov_b32_e32 v3, s10
	v_readlane_b32 s10, v255, 13
	v_readlane_b32 s11, v255, 14
	s_nop 4
	global_atomic_add v3, v2, v3, s[10:11] sc0
